# LRU chunk loop: 16 scan outputs rounded with 8 v_cvt_pk_bf16_f32 instead of the 32-op bit trick
# speedup vs baseline: 1.0078x; 1.0003x over previous
.LBB0_337:
	s_and_b32 s16, s0, 0x4000
	v_cndmask_b32_e64 v34, v68, 1.0, s[4:5]
	v_add_u32_e32 v68, s16, v188
	s_waitcnt lgkmcnt(0)
	s_barrier
	v_add_u32_e32 v1, v68, v191
	ds_read_b128 v[172:175], v1 offset:42240
	v_add_u32_e32 v0, 0x7ff, v0
	v_add_u32_e32 v68, v68, v194
	v_cndmask_b32_e64 v0, v0, v123, s[12:13]
	ds_read_b128 v[214:217], v68 offset:42240
	v_mov_b32_e32 v1, v32
	v_lshlrev_b64 v[0:1], 10, v[0:1]
	v_lshl_add_u64 v[0:1], v[166:167], 0, v[0:1]
	v_add_u32_e32 v68, s33, v186
	s_waitcnt lgkmcnt(1)
	global_store_dwordx4 v[0:1], v[172:175], off nt
	ds_read2st64_b64 v[172:175], v68 offset0:72 offset1:73
	v_cndmask_b32_e64 v35, v131, v70, s[4:5]
	v_cndmask_b32_e64 v131, v139, v133, s[4:5]
	v_cndmask_b32_e64 v33, v69, 0, s[4:5]
	v_cndmask_b32_e64 v129, v135, v129, s[4:5]
	s_waitcnt lgkmcnt(0)
	v_fma_f32 v139, v172, v71, v173
	v_cndmask_b32_e64 v135, v147, v141, s[4:5]
	v_cndmask_b32_e64 v141, v71, v139, s[6:7]
	ds_read2st64_b64 v[68:71], v68 offset0:74 offset1:75
	v_add_u32_e32 v0, s14, v207
	v_cndmask_b32_e64 v0, v0, v121, s[12:13]
	v_mov_b32_e32 v1, v32
	v_lshlrev_b64 v[0:1], 10, v[0:1]
	v_lshl_add_u64 v[0:1], v[166:167], 0, v[0:1]
	v_fmac_f32_e32 v175, v174, v139
	global_store_dwordx4 v[0:1], v[214:217], off nt
	v_cndmask_b32_e64 v0, v141, v175, s[8:9]
	s_waitcnt lgkmcnt(0)
	v_fma_f32 v1, v68, v175, v69
	v_cndmask_b32_e64 v0, v0, v1, s[10:11]
	v_fmac_f32_e32 v33, v34, v0
	v_fmac_f32_e32 v18, v16, v33
	v_fmac_f32_e32 v17, v2, v33
	v_cvt_pk_bf16_f32 v16, v18, v17
	v_add_u32_e32 v18, s19, v195
	v_fmac_f32_e32 v3, v125, v33
	v_fmac_f32_e32 v19, v127, v33
	ds_write_b16 v18, v16 offset:42240
	ds_write_b16_d16_hi v18, v16 offset:42368
	v_cvt_pk_bf16_f32 v2, v3, v19
	v_fmac_f32_e32 v35, v129, v0
	v_fmac_f32_e32 v5, v4, v35
	ds_write_b16 v18, v2 offset:42496
	ds_write_b16_d16_hi v18, v2 offset:42624
	v_fmac_f32_e32 v6, v20, v35
	v_cvt_pk_bf16_f32 v16, v5, v6
	v_fmac_f32_e32 v7, v22, v35
	v_cndmask_b32_e64 v133, v143, v137, s[4:5]
	v_cndmask_b32_e64 v137, v149, v145, s[4:5]
	v_fmac_f32_e32 v21, v23, v35
	ds_write_b16 v18, v16 offset:43264
	ds_write_b16_d16_hi v18, v16 offset:43392
	v_cvt_pk_bf16_f32 v2, v7, v21
	v_fmac_f32_e32 v131, v133, v0
	v_fmac_f32_e32 v135, v137, v0
	ds_write_b16 v18, v2 offset:43520
	ds_write_b16_d16_hi v18, v2 offset:43648
	v_fmac_f32_e32 v9, v8, v131
	v_fmac_f32_e32 v13, v12, v135
	v_fmac_f32_e32 v10, v24, v131
	v_fmac_f32_e32 v14, v28, v135
	v_cvt_pk_bf16_f32 v16, v9, v10
	v_cvt_pk_bf16_f32 v0, v13, v14
	v_fmac_f32_e32 v11, v26, v131
	v_fmac_f32_e32 v15, v30, v135
	ds_write_b16 v18, v16 offset:44288
	ds_write_b16_d16_hi v18, v16 offset:44416
	ds_write_b16 v18, v0 offset:45312
	ds_write_b16_d16_hi v18, v0 offset:45440
	v_fmac_f32_e32 v25, v27, v131
	v_fmac_f32_e32 v29, v31, v135
	s_addk_i32 s14, 0xff80
	s_addk_i32 s0, 0x4000
	v_cvt_pk_bf16_f32 v2, v11, v25
	v_cvt_pk_bf16_f32 v16, v15, v29
	v_fmac_f32_e32 v71, v70, v1
	v_add_u32_e32 v123, 0x80, v123
	s_cmpk_lg_i32 s14, 0xf900
	v_add_u32_e32 v121, 0x80, v121
	ds_write_b16 v18, v2 offset:44544
	ds_write_b16_d16_hi v18, v2 offset:44672
	ds_write_b16 v18, v16 offset:45568
	ds_write_b16_d16_hi v18, v16 offset:45696
	s_cbranch_scc0 .LBB0_339
	s_mov_b32 s18, s15
	s_branch .LBB0_317
